# NSA block-selection bit search: cross-lane count via DPP adds instead of 3 LDS bpermute round trips per step
# speedup vs baseline: 1.0023x; 1.0023x over previous
.LBB0_840:
	s_lshl_b32 s1, 1, s0
	v_or_b32_e32 v55, s1, v32
	s_waitcnt lgkmcnt(7)
	v_cmp_ge_u32_e32 vcc, v49, v55
	s_add_i32 s0, s0, -1
	s_cmp_eq_u32 s0, -1
	v_cndmask_b32_e64 v56, 0, 1, vcc
	v_cmp_ge_u32_e32 vcc, v48, v55
	s_nop 1
	v_addc_co_u32_e32 v56, vcc, 0, v56, vcc
	s_waitcnt lgkmcnt(6)
	v_cmp_ge_u32_e32 vcc, v46, v55
	s_nop 1
	v_cndmask_b32_e64 v57, 0, 1, vcc
	v_cmp_ge_u32_e32 vcc, v47, v55
	s_nop 1
	v_addc_co_u32_e32 v56, vcc, v56, v57, vcc
	s_waitcnt lgkmcnt(5)
	v_cmp_ge_u32_e32 vcc, v44, v55
	s_nop 1
	v_cndmask_b32_e64 v57, 0, 1, vcc
	v_cmp_ge_u32_e32 vcc, v45, v55
	s_nop 1
	v_addc_co_u32_e32 v56, vcc, v56, v57, vcc
	s_waitcnt lgkmcnt(4)
	v_cmp_ge_u32_e32 vcc, v42, v55
	s_nop 1
	v_cndmask_b32_e64 v57, 0, 1, vcc
	v_cmp_ge_u32_e32 vcc, v43, v55
	s_nop 1
	v_addc_co_u32_e32 v56, vcc, v56, v57, vcc
	s_waitcnt lgkmcnt(3)
	v_cmp_ge_u32_e32 vcc, v40, v55
	s_nop 1
	v_cndmask_b32_e64 v57, 0, 1, vcc
	v_cmp_ge_u32_e32 vcc, v41, v55
	s_nop 1
	v_addc_co_u32_e32 v56, vcc, v56, v57, vcc
	s_waitcnt lgkmcnt(2)
	v_cmp_ge_u32_e32 vcc, v38, v55
	s_nop 1
	v_cndmask_b32_e64 v57, 0, 1, vcc
	v_cmp_ge_u32_e32 vcc, v39, v55
	s_nop 1
	v_addc_co_u32_e32 v56, vcc, v56, v57, vcc
	s_waitcnt lgkmcnt(1)
	v_cmp_ge_u32_e32 vcc, v36, v55
	s_nop 1
	v_cndmask_b32_e64 v57, 0, 1, vcc
	v_cmp_ge_u32_e32 vcc, v37, v55
	s_nop 1
	v_addc_co_u32_e32 v56, vcc, v56, v57, vcc
	s_waitcnt lgkmcnt(0)
	v_cmp_ge_u32_e32 vcc, v34, v55
	s_nop 1
	v_cndmask_b32_e64 v57, 0, 1, vcc
	v_cmp_ge_u32_e32 vcc, v35, v55
	s_nop 1
	v_addc_co_u32_e32 v56, vcc, v56, v57, vcc
	s_nop 1
	v_add_u32_dpp v56, v56, v56 quad_perm:[1,0,3,2] row_mask:0xf bank_mask:0xf
	s_nop 1
	v_add_u32_dpp v56, v56, v56 quad_perm:[2,3,0,1] row_mask:0xf bank_mask:0xf
	s_nop 1
	v_add_u32_dpp v56, v56, v56 row_half_mirror row_mask:0xf bank_mask:0xf
	v_cmp_lt_i32_e32 vcc, 15, v56
	s_nop 1
	v_cndmask_b32_e32 v32, v32, v55, vcc
	s_cbranch_scc0 .LBB0_840
	v_cmp_lt_u32_e32 vcc, v48, v32
	v_cmp_eq_u32_e64 s[0:1], 0, v48
	v_lshlrev_b32_e64 v48, v51, 1
	s_or_b64 s[0:1], s[0:1], vcc
	v_cndmask_b32_e64 v52, v48, 0, s[0:1]
	v_cmp_lt_u32_e32 vcc, v49, v32
	v_cmp_eq_u32_e64 s[0:1], 0, v49
	s_movk_i32 s6, 0x100
	v_lshlrev_b32_e64 v49, v51, s6
	s_or_b64 s[0:1], s[0:1], vcc
	v_cndmask_b32_e64 v53, v49, 0, s[0:1]
	v_cmp_lt_u32_e32 vcc, v46, v32
	v_cmp_eq_u32_e64 s[0:1], 0, v46
	s_mov_b32 s6, 0x10000
	v_or_b32_e32 v53, v52, v53
	v_lshlrev_b32_e64 v52, v51, s6
	s_or_b64 s[0:1], s[0:1], vcc
	v_cndmask_b32_e64 v46, v52, 0, s[0:1]
	v_cmp_lt_u32_e32 vcc, v47, v32
	v_cmp_eq_u32_e64 s[0:1], 0, v47
	s_mov_b32 s6, 0x1000000
	v_lshlrev_b32_e64 v47, v51, s6
	s_or_b64 s[0:1], s[0:1], vcc
	v_cndmask_b32_e64 v51, v47, 0, s[0:1]
	v_or3_b32 v51, v53, v46, v51
	v_lshlrev_b32_e32 v46, 4, v50
	v_cmp_ne_u32_e32 vcc, 0, v51
	s_and_saveexec_b64 s[0:1], vcc
	ds_or_b32 v46, v51 offset:51840
	s_or_b64 exec, exec, s[0:1]
	v_cmp_lt_u32_e32 vcc, v44, v32
	v_cmp_eq_u32_e64 s[0:1], 0, v44
	s_or_b64 s[0:1], s[0:1], vcc
	v_cmp_lt_u32_e32 vcc, v45, v32
	v_cndmask_b32_e64 v44, v48, 0, s[0:1]
	v_cmp_eq_u32_e64 s[0:1], 0, v45
	s_or_b64 s[0:1], s[0:1], vcc
	v_cmp_lt_u32_e32 vcc, v42, v32
	v_cndmask_b32_e64 v45, v49, 0, s[0:1]
	v_cmp_eq_u32_e64 s[0:1], 0, v42
	s_or_b64 s[0:1], s[0:1], vcc
	v_cmp_lt_u32_e32 vcc, v43, v32
	v_cndmask_b32_e64 v42, v52, 0, s[0:1]
	v_cmp_eq_u32_e64 s[0:1], 0, v43
	s_or_b64 s[0:1], s[0:1], vcc
	v_or_b32_e32 v44, v44, v45
	v_cndmask_b32_e64 v43, v47, 0, s[0:1]
	v_or3_b32 v42, v44, v42, v43
	v_cmp_ne_u32_e32 vcc, 0, v42
	s_and_saveexec_b64 s[0:1], vcc
	ds_or_b32 v46, v42 offset:51844
	s_or_b64 exec, exec, s[0:1]
	v_cmp_lt_u32_e32 vcc, v40, v32
	v_cmp_eq_u32_e64 s[0:1], 0, v40
	s_or_b64 s[0:1], s[0:1], vcc
	v_cmp_lt_u32_e32 vcc, v41, v32
	v_cndmask_b32_e64 v40, v48, 0, s[0:1]
	v_cmp_eq_u32_e64 s[0:1], 0, v41
	s_or_b64 s[0:1], s[0:1], vcc
	v_cmp_lt_u32_e32 vcc, v38, v32
	v_cndmask_b32_e64 v41, v49, 0, s[0:1]
	v_cmp_eq_u32_e64 s[0:1], 0, v38
	s_or_b64 s[0:1], s[0:1], vcc
	v_cmp_lt_u32_e32 vcc, v39, v32
	v_cndmask_b32_e64 v38, v52, 0, s[0:1]
	v_cmp_eq_u32_e64 s[0:1], 0, v39
	s_or_b64 s[0:1], s[0:1], vcc
	v_or_b32_e32 v40, v40, v41
	v_cndmask_b32_e64 v39, v47, 0, s[0:1]
	v_or3_b32 v38, v40, v38, v39
	v_cmp_ne_u32_e32 vcc, 0, v38
	s_and_saveexec_b64 s[0:1], vcc
	ds_or_b32 v46, v38 offset:51848
	s_or_b64 exec, exec, s[0:1]
	v_cmp_lt_u32_e32 vcc, v36, v32
	v_cmp_eq_u32_e64 s[0:1], 0, v36
	s_or_b64 s[0:1], s[0:1], vcc
	v_cmp_lt_u32_e32 vcc, v37, v32
	v_cndmask_b32_e64 v36, v48, 0, s[0:1]
	v_cmp_eq_u32_e64 s[0:1], 0, v37
	s_or_b64 s[0:1], s[0:1], vcc
	v_cmp_lt_u32_e32 vcc, v34, v32
	v_cndmask_b32_e64 v37, v49, 0, s[0:1]
	v_cmp_eq_u32_e64 s[0:1], 0, v34
	s_or_b64 s[0:1], s[0:1], vcc
	v_cmp_lt_u32_e32 vcc, v35, v32
	v_cndmask_b32_e64 v34, v52, 0, s[0:1]
	v_cmp_eq_u32_e64 s[0:1], 0, v35
	s_or_b64 s[0:1], s[0:1], vcc
	v_or_b32_e32 v36, v36, v37
	v_cndmask_b32_e64 v32, v47, 0, s[0:1]
	v_or3_b32 v32, v36, v34, v32
	v_cmp_ne_u32_e32 vcc, 0, v32
	s_and_saveexec_b64 s[0:1], vcc
	ds_or_b32 v46, v32 offset:51852
	s_or_b64 exec, exec, s[0:1]
	v_pk_fma_f32 v[16:17], v[160:161], v[16:17], 0 op_sel_hi:[0,1,0]
	v_pk_fma_f32 v[0:1], v[160:161], v[0:1], 0 op_sel_hi:[0,1,0]
	v_cvt_pk_bf16_f32 v172, v16, v17
	v_pk_fma_f32 v[16:17], v[160:161], v[18:19], 0 op_sel_hi:[0,1,0]
	v_cvt_pk_bf16_f32 v180, v0, v1
	v_pk_fma_f32 v[0:1], v[160:161], v[2:3], 0 op_sel_hi:[0,1,0]
	v_cvt_pk_bf16_f32 v173, v16, v17
	v_pk_fma_f32 v[16:17], v[160:161], v[20:21], 0 op_sel_hi:[0,1,0]
	v_cvt_pk_bf16_f32 v181, v0, v1
	v_pk_fma_f32 v[0:1], v[160:161], v[4:5], 0 op_sel_hi:[0,1,0]
	v_cvt_pk_bf16_f32 v174, v16, v17
	v_pk_fma_f32 v[16:17], v[160:161], v[22:23], 0 op_sel_hi:[0,1,0]
	v_cvt_pk_bf16_f32 v182, v0, v1
	v_pk_fma_f32 v[0:1], v[160:161], v[6:7], 0 op_sel_hi:[0,1,0]
	v_cvt_pk_bf16_f32 v175, v16, v17
	v_pk_fma_f32 v[16:17], v[160:161], v[24:25], 0 op_sel_hi:[0,1,0]
	v_cvt_pk_bf16_f32 v183, v0, v1
	v_pk_fma_f32 v[0:1], v[160:161], v[8:9], 0 op_sel_hi:[0,1,0]
	s_max_i32 s0, s21, 0x1ff
	v_cvt_pk_bf16_f32 v176, v16, v17
	v_pk_fma_f32 v[16:17], v[160:161], v[26:27], 0 op_sel_hi:[0,1,0]
	v_cvt_pk_bf16_f32 v186, v0, v1
	v_pk_fma_f32 v[0:1], v[160:161], v[10:11], 0 op_sel_hi:[0,1,0]
	s_addk_i32 s0, 0xfe01
	v_readlane_b32 s48, v249, 26
	v_cvt_pk_bf16_f32 v177, v16, v17
	v_pk_fma_f32 v[16:17], v[160:161], v[28:29], 0 op_sel_hi:[0,1,0]
	v_cvt_pk_bf16_f32 v187, v0, v1
	v_pk_fma_f32 v[0:1], v[160:161], v[12:13], 0 op_sel_hi:[0,1,0]
	s_lshr_b32 s22, s0, 7
	s_lshl_b64 s[6:7], s[2:3], 20
	s_lshr_b32 s23, s12, 2
	s_add_i32 s24, s21, 0xfffffe1f
	v_readlane_b32 s50, v249, 28
	v_cvt_pk_bf16_f32 v178, v16, v17
	v_pk_fma_f32 v[16:17], v[160:161], v[30:31], 0 op_sel_hi:[0,1,0]
	v_cvt_pk_bf16_f32 v184, v0, v1
	v_pk_fma_f32 v[0:1], v[160:161], v[14:15], 0 op_sel_hi:[0,1,0]
	v_readlane_b32 s51, v249, 29
	s_add_u32 s8, s50, s6
	v_cvt_pk_bf16_f32 v179, v16, v17
	v_cvt_pk_bf16_f32 v185, v0, v1
	s_addc_u32 s9, s51, s7
	v_add_u32_e32 v160, s21, v196
	s_mov_b64 s[0:1], 0x800000
	s_mov_b64 s[12:13], -1
	s_mov_b64 s[10:11], 0
	s_waitcnt lgkmcnt(0)
	s_barrier
	v_readlane_b32 s49, v249, 27
	v_readlane_b32 s52, v249, 30
	v_readlane_b32 s53, v249, 31
	v_readlane_b32 s54, v249, 32
	v_readlane_b32 s55, v249, 33
	v_readlane_b32 s56, v249, 34
	v_readlane_b32 s57, v249, 35
	v_readlane_b32 s58, v249, 36
	v_readlane_b32 s59, v249, 37
	v_readlane_b32 s60, v249, 38
	v_readlane_b32 s61, v249, 39
	v_readlane_b32 s62, v249, 40
	v_readlane_b32 s63, v249, 41
